# attention staging: next-tile row loads use two address registers with immediate offsets
# speedup vs baseline: 1.0033x; 1.0033x over previous
.LBB0_377:
	s_cmp_ge_i32 s16, s11
	s_cbranch_scc1 .LBB0_379
	s_or_b32 s16, s16, 1
	s_add_i32 s17, s16, s22
	s_sub_i32 s33, s38, s16
	s_cmp_lt_i32 s16, s23
	s_cselect_b32 s16, s17, s33
	s_lshl_b32 s16, s16, 6
	s_ashr_i32 s17, s16, 31
	s_lshl_b64 s[74:75], s[16:17], 8
	s_add_u32 s74, s74, 0x1000
	s_addc_u32 s75, s75, 0
	v_lshl_add_u64 v[14:15], v[170:171], 0, s[74:75]
	s_add_u32 s74, s74, 0x2000
	s_addc_u32 s75, s75, 0
	v_lshl_add_u64 v[98:99], v[170:171], 0, s[74:75]
	global_load_dwordx4 v[146:149], v[14:15], off offset:-4096
	global_load_dwordx4 v[150:153], v[14:15], off
	global_load_dwordx4 v[154:157], v[98:99], off offset:-4096
	global_load_dwordx4 v[158:161], v[98:99], off

.LBB0_391:
	s_cmp_ge_i32 s16, s11
	s_cbranch_scc1 .LBB0_393
	s_add_i32 s17, s16, 1
	s_not_b32 s16, s16
	s_add_i32 s33, s17, s22
	s_add_i32 s16, s38, s16
	s_cmp_lt_i32 s17, s23
	s_cselect_b32 s16, s33, s16
	s_lshl_b32 s16, s16, 6
	s_ashr_i32 s17, s16, 31
	s_lshl_b64 s[72:73], s[16:17], 8
	s_add_u32 s72, s72, 0x1000
	s_addc_u32 s73, s73, 0
	v_lshl_add_u64 v[14:15], v[170:171], 0, s[72:73]
	s_add_u32 s72, s72, 0x2000
	s_addc_u32 s73, s73, 0
	v_lshl_add_u64 v[98:99], v[170:171], 0, s[72:73]
	global_load_dwordx4 v[146:149], v[14:15], off offset:-4096
	global_load_dwordx4 v[150:153], v[14:15], off
	global_load_dwordx4 v[154:157], v[98:99], off offset:-4096
	global_load_dwordx4 v[158:161], v[98:99], off
